# P5 epilogue: row-scale ssq loads prefetched one tile ahead (no vmcnt0 stall)
# speedup vs baseline: 1.0028x; 1.0028x over previous
;     __device__ __forceinline__ unsigned voffA(int R, int C) const { return (unsigned)(R * lda + C) * 2u; }
;     __device__ __forceinline__ unsigned voffB(int R, int C) const { return (unsigned)(R * ldb + C) * 2u; }
;     __device__ __forceinline__ size_t hA() const { return (size_t)HALF * lda * 2; }
;     __device__ __forceinline__ size_t hB() const { return (size_t)HALF * ldb * 2; }
;     __device__ __forceinline__ const char* a(const Unit& u) const { return (const char*)A + (size_t)u.pm * 2 * hA(); }
;     __device__ __forceinline__ const char* b(const Unit& u) const { return (const char*)Bt + (size_t)u.pn * 2 * hB() + (size_t)(u.pm >> gshift) * goff; }
;     __device__ __forceinline__ void operator()(const f32x4 (&acc)[2][2][4][2], const Unit& u, int wr, int wc, int fr, int fq) const {
;     ...
;         float rsv[2][4];
; #pragma unroll
;         for (int ai = 0; ai < 2; ++ai)
; #pragma unroll
;             for (int m = 0; m < 4; ++m) rsv[ai][m] = RS ? rs[row0 + ai * HALF + m * 16] : 1.0f;
;     ...
;     for (int i = 0; i < 2; ++i) { int R, C; stage_rc(tid * 16 + i * 8192, R, C); const int Rb = Epi::PERM ? ((R & ~31) + perm32(R & 31)) : R;
;         voffA[i] = g.voffA(R, C); voffB[i] = g.voffB(Rb, C); }
;     const size_t kstep = (size_t)(BK * 2);
;     const size_t hstepA = g.hA(), hstepB = g.hB();
;     const unsigned ldsw = (unsigned)wid * 1024u;
;     const int aoff = lds_byte(wr * 64 + fr, fq * 8), boff = lds_byte(wc * 32 + fr, fq * 8);
;     ...
;     Unit cur, nxt; int ui = 0;
;     if (!S.next(0, cur)) return;
;     f32x4 acc[2][2][4][2];
; #pragma unroll
;     for (int a = 0; a < 2; ++a)
; #pragma unroll
;         for (int b = 0; b < 2; ++b)
; #pragma unroll
;             for (int m = 0; m < 4; ++m)
; #pragma unroll
;                 for (int n = 0; n < 2; ++n) acc[a][b][m][n] = (f32x4){0.f, 0.f, 0.f, 0.f};
;     bf16x8 At[4][2], B0[2][2], B1[2][2];
;     const char* cA = g.a(cur); const char* cB = g.b(cur);
;     S.a_ready(cur);
;     PG8_STAGE(PG8_SB(0, 0), cB, voffB); PG8_STAGE(PG8_SB(0, 1), cB + hstepB, voffB); PG8_STAGE(PG8_SA(0, 0), cA, voffA); PG8_STAGE(PG8_SA(0, 1), cA + hstepA, voffA);
;     if (wr == 1) PG8_BAR;
;     PG8_WAIT_V(2); PG8_BAR;
;     PG8_STAGE(PG8_SB(1, 0), cB + kstep, voffB); PG8_STAGE(PG8_SA(1, 0), cA + kstep, voffA); PG8_STAGE(PG8_SB(1, 1), cB + hstepB + kstep, voffB);
;     PG8_WAIT_V(6); PG8_BAR;
.LBB0_703:
	v_readlane_b32 s0, v254, 40
	v_readlane_b32 s1, v254, 41
	s_and_b64 s[0:1], s[0:1], s[20:21]
	s_and_b64 s[0:1], s[0:1], exec
	v_readlane_b32 s0, v254, 20
	v_readlane_b32 s1, v254, 21
	s_cselect_b32 s77, s1, s69
	s_cselect_b32 s76, s0, s68
	s_lshl_b64 s[0:1], s[78:79], 12
	s_add_u32 s30, s74, s0
	s_mov_b32 s0, s70
	s_addc_u32 s31, s75, s1
	v_mbcnt_lo_u32_b32 v0, s0, 0
	v_mbcnt_hi_u32_b32 v0, s0, v0
	v_readlane_b32 s0, v254, 22
	v_readlane_b32 s1, v254, 23
	s_and_b64 vcc, exec, s[0:1]
	s_cbranch_vccnz .LBB0_723
	v_readlane_b32 s98, v254, 36
	v_readlane_b32 s99, v254, 37
	s_lshl_b64 s[100:101], s[78:79], 2
	s_add_u32 s98, s98, s100
	s_addc_u32 s99, s99, s101
	v_readlane_b32 s100, v255, 19
	s_lshl_b32 s100, s100, 8
	s_add_i32 s100, s100, s48
	v_and_or_b32 v248, v0, 15, s100
	v_mov_b32_e32 v249, 0
	v_lshl_add_u64 v[248:249], v[248:249], 2, s[98:99]
	global_load_dword v240, v[248:249], off
	global_load_dword v241, v[248:249], off offset:64
	global_load_dword v242, v[248:249], off offset:128
	global_load_dword v243, v[248:249], off offset:192
	global_load_dword v244, v[248:249], off offset:512
	global_load_dword v245, v[248:249], off offset:576
	global_load_dword v246, v[248:249], off offset:640
	global_load_dword v247, v[248:249], off offset:704
	v_lshl_add_u32 v1, v0, 4, s33
	v_ashrrev_i32_e32 v2, 31, v1
	v_lshrrev_b32_e32 v2, 22, v2
	v_add_u32_e32 v2, v1, v2
	v_ashrrev_i32_e32 v2, 10, v2
	v_mul_i32_i24_e32 v3, 0x400, v2
	v_sub_u32_e32 v3, v1, v3
	v_lshrrev_b32_e32 v4, 4, v3
	v_bitop3_b32 v3, v4, v3, 32 bitop3:0x6c
	v_ashrrev_i32_e32 v5, 31, v3
	v_lshrrev_b32_e32 v5, 26, v5
	v_lshlrev_b32_e32 v4, 3, v2
	v_add_u32_e32 v5, v3, v5
	v_and_b32_e32 v4, -16, v4
	v_ashrrev_i32_e32 v6, 6, v5
	v_and_b32_e32 v5, 0xc0, v5
	v_add_u32_e32 v4, v6, v4
	v_sub_u32_e32 v3, v3, v5
	v_lshlrev_b32_e32 v2, 5, v2
	v_ashrrev_i16_sdwa v3, v228, sext(v3) dst_sel:DWORD dst_unused:UNUSED_PAD src0_sel:DWORD src1_sel:BYTE_0
	v_lshlrev_b32_e32 v5, 1, v4
	v_lshrrev_b32_e32 v7, 2, v4
	v_and_b32_e32 v6, 3, v6
	s_mov_b32 s0, 0xfffe0
	v_and_b32_e32 v2, 32, v2
	v_bfe_i32 v3, v3, 0, 16
	v_and_b32_e32 v5, 24, v5
	v_and_b32_e32 v7, 4, v7
	v_and_or_b32 v6, v4, s0, v6
	v_or3_b32 v5, v6, v7, v5
	v_add_lshl_u32 v2, v2, v3, 1
	v_add_u32_e32 v1, 0x2000, v1
	v_lshl_add_u32 v128, v4, 12, v2
	v_lshl_add_u32 v192, v5, 12, v2
	v_ashrrev_i32_e32 v2, 31, v1
	v_lshrrev_b32_e32 v2, 22, v2
	v_add_u32_e32 v2, v1, v2
	v_ashrrev_i32_e32 v2, 10, v2
	v_mul_i32_i24_e32 v3, 0x400, v2
	v_sub_u32_e32 v1, v1, v3
	v_lshrrev_b32_e32 v3, 4, v1
	v_bitop3_b32 v1, v3, v1, 32 bitop3:0x6c
	v_ashrrev_i32_e32 v4, 31, v1
	v_lshrrev_b32_e32 v4, 26, v4
	v_add_u32_e32 v4, v1, v4
	v_ashrrev_i32_e32 v5, 6, v4
	v_and_b32_e32 v4, 0xffc0, v4
	v_sub_u32_e32 v1, v1, v4
	v_lshlrev_b32_e32 v3, 3, v2
	v_lshrrev_b16_e32 v4, 7, v1
	v_and_b32_e32 v3, -16, v3
	v_and_b32_e32 v4, 1, v4
	v_add_u32_e32 v3, v5, v3
	v_add_u16_e32 v1, v1, v4
	v_lshlrev_b32_e32 v2, 5, v2
	v_ashrrev_i16_sdwa v1, v228, sext(v1) dst_sel:DWORD dst_unused:UNUSED_PAD src0_sel:DWORD src1_sel:BYTE_0
	v_lshlrev_b32_e32 v4, 1, v3
	v_lshrrev_b32_e32 v6, 2, v3
	v_and_b32_e32 v5, 3, v5
	v_and_b32_e32 v2, 32, v2
	v_bfe_i32 v1, v1, 0, 16
	v_and_b32_e32 v4, 24, v4
	v_and_b32_e32 v6, 4, v6
	v_and_or_b32 v5, v3, s0, v5
	s_add_i32 s0, s33, 0
	v_readlane_b32 s20, v255, 25
	v_or3_b32 v4, v5, v6, v4
	v_add_lshl_u32 v1, v2, v1, 1
	s_add_i32 m0, s0, 0x10000
	v_readlane_b32 s21, v255, 26
	v_lshl_add_u32 v132, v4, 12, v1
	v_lshl_add_u32 v130, v3, 12, v1
	v_cmp_ne_u32_e64 s[38:39], 1, v226
	s_nop 1
	global_load_lds_dwordx4 v192, s[20:21]
	s_add_i32 m0, s0, 0x12000
	s_nop 0
	global_load_lds_dwordx4 v132, s[20:21]
	v_readlane_b32 s20, v255, 23
	s_add_i32 m0, s0, 0x14000
	v_readlane_b32 s21, v255, 24
	s_nop 4
	global_load_lds_dwordx4 v192, s[20:21]
	s_add_i32 m0, s0, 0x16000
	s_nop 0
	global_load_lds_dwordx4 v132, s[20:21]
	v_readlane_b32 s20, v255, 21
	v_readlane_b32 s21, v255, 22
	s_add_u32 s46, s30, s20
	s_addc_u32 s47, s31, s21
	s_add_i32 s1, s0, 0x2000
	s_mov_b32 m0, s0
	s_add_u32 s20, s46, 0x80000
	global_load_lds_dwordx4 v128, s[46:47]
	s_mov_b32 m0, s1
	s_addc_u32 s21, s47, 0
	s_add_i32 s34, s0, 0x4000
	global_load_lds_dwordx4 v130, s[46:47]
	s_mov_b32 m0, s34
	s_add_i32 s35, s0, 0x6000
	global_load_lds_dwordx4 v128, s[20:21]
	s_mov_b32 m0, s35
	s_nop 0
	global_load_lds_dwordx4 v130, s[20:21]
	v_readlane_b32 s20, v254, 26
	v_readlane_b32 s21, v254, 27
	s_andn2_b64 vcc, exec, s[20:21]
	s_cbranch_vccnz .LBB0_706
	s_barrier

;     __device__ __forceinline__ const char* a(const Unit& u) const { return (const char*)A + (size_t)u.pm * 2 * hA(); }
;     __device__ __forceinline__ const char* b(const Unit& u) const { return (const char*)Bt + (size_t)u.pn * 2 * hB() + (size_t)(u.pm >> gshift) * goff; }
;     __device__ __forceinline__ const char* a(const Unit& u) const { return (const char*)A + (size_t)u.pm * 2 * hA(); }
;     __device__ __forceinline__ const char* b(const Unit& u) const { return (const char*)Bt + (size_t)((u.pn >> 4) * 4096 + (u.pn & 15) * 16) * 1024 * 2 + (size_t)(u.pm >> 1) * 512; }
;     __device__ __forceinline__ void operator()(const f32x4 (&acc)[2][2][4][2], const Unit& u, int wr, int wc, int fr, int fq) const {
;     ...
;         float rsv[2][4];
; #pragma unroll
;         for (int ai = 0; ai < 2; ++ai)
; #pragma unroll
;             for (int m = 0; m < 4; ++m) rsv[ai][m] = RS ? rs[row0 + ai * HALF + m * 16] : 1.0f;
; #pragma unroll
;         for (int ai = 0; ai < 2; ++ai)
; #pragma unroll
;             for (int m = 0; m < 4; ++m) { const int r = row0 + ai * HALF + m * 16;
;                 bf16_t* rowp = hm ? base + ((size_t)((r >> 12) * 8 + (colt >> 7)) * 4096 + (r & 4095)) * 128 + wc * 32 + 8 * fq : base + (size_t)r * ldc + col0;
;                 float rv = sc; if (RS == 1) rv *= rsv[ai][m]; if (RS == 2) rv *= __builtin_amdgcn_rsqf(rsv[ai][m] * (1.0f / DM) + EPS);
; #pragma unroll
;                 for (int bj = 0; bj < 2; ++bj) { f32x4 v0 = acc[ai][bj][m][0] * rv, v1 = acc[ai][bj][m][1] * rv;
;                     if (CS) { v0 = v0 * cv[bj][0]; v1 = v1 * cv[bj][1]; }
;                     if (ACT == 2) {
; #pragma unroll
;                         for (int e = 0; e < 4; ++e) { float a = v0[e] > 0.f ? v0[e] : 0.f, b = v1[e] > 0.f ? v1[e] : 0.f; v0[e] = a * a; v1[e] = b * b; } }
;                     if (k8) {
;                         u32x2 w8; w8.x = pk_fp8x4(v0); w8.y = pk_fp8x4(v1);
;                         *(u32x2*)((unsigned char*)base + ((size_t)((r >> 12) * 8 + (colt >> 7) + bj) * 4096 + (r & 4095)) * 128 + wc * 32 + 8 * fq) = w8;
;                     } else {
;                     u32x4 w; w.x = cvt_pk_bf16(v0[0], v0[1]); w.y = cvt_pk_bf16(v0[2], v0[3]); w.z = cvt_pk_bf16(v1[0], v1[1]); w.w = cvt_pk_bf16(v1[2], v1[3]);
;                     *(u32x4*)(rowp + bj * bstep) = w; } } }
.LBB0_719:
	s_mov_b32 s21, s70
	s_lshl_b32 s22, s74, 8
	v_mbcnt_lo_u32_b32 v133, s21, 0
	v_mbcnt_hi_u32_b32 v133, s21, v133
	s_add_i32 s22, s22, s48
	s_lshl_b32 s21, s75, 8
	v_and_or_b32 v134, v133, 15, s22
	v_ashrrev_i32_e32 v135, 31, v134
	v_lshl_add_u64 v[138:139], v[134:135], 2, s[24:25]
	v_mov_b32_e32 v150, v240
	v_mov_b32_e32 v151, v241
	v_mov_b32_e32 v148, v242
	v_ashrrev_i32_e32 v133, 1, v133
	v_and_b32_e32 v149, -8, v133
	v_mov_b32_e32 v147, v243
	v_mov_b32_e32 v146, v244
	v_mov_b32_e32 v145, v245
	v_mov_b32_e32 v144, v246
	v_mov_b32_e32 v133, v247
	s_cmp_lg_u64 s[40:41], 0
	s_cselect_b32 s98, s36, s74
	s_lshl_b32 s98, s98, 8
	s_add_i32 s98, s98, s48
	v_and_or_b32 v248, v134, 15, s98
	v_mov_b32_e32 v249, 0
	v_lshl_add_u64 v[248:249], v[248:249], 2, s[24:25]
	global_load_dword v240, v[248:249], off
	global_load_dword v241, v[248:249], off offset:64
	global_load_dword v242, v[248:249], off offset:128
	global_load_dword v243, v[248:249], off offset:192
	global_load_dword v244, v[248:249], off offset:512
	global_load_dword v245, v[248:249], off offset:576
	global_load_dword v246, v[248:249], off offset:640
	global_load_dword v247, v[248:249], off offset:704
	s_or_b32 s21, s21, s50
	v_add_u32_e32 v138, s21, v149
	v_ashrrev_i32_e32 v139, 31, v138
	v_or_b32_e32 v142, 16, v134
	v_or_b32_e32 v140, 32, v134
	v_or_b32_e32 v136, 48, v134
	v_lshl_add_u64 v[138:139], v[138:139], 1, s[76:77]
	v_lshlrev_b64 v[134:135], 14, v[134:135]
	v_lshl_add_u64 v[134:135], v[138:139], 0, v[134:135]
	v_ashrrev_i32_e32 v143, 31, v142
	v_ashrrev_i32_e32 v141, 31, v140
	v_ashrrev_i32_e32 v137, 31, v136
	s_mov_b32 s21, 0x200000
	s_mov_b64 s[22:23], 0x200000
	v_fmamk_f32 v149, v150, 0x3a000000, v227
	v_rsq_f32_e32 v150, v149
	s_nop 0
	v_pk_mul_f32 v[120:121], v[120:121], v[150:151] op_sel_hi:[1,0]
	v_pk_mul_f32 v[124:125], v[124:125], v[150:151] op_sel_hi:[1,0]
	v_pk_mul_f32 v[122:123], v[122:123], v[150:151] op_sel_hi:[1,0]
	v_max_f32_e32 v120, 0, v120
	v_pk_mul_f32 v[126:127], v[126:127], v[150:151] op_sel_hi:[1,0]
	v_mul_f32_e32 v149, v120, v120
	v_max_f32_e32 v120, 0, v125
	v_max_f32_e32 v121, 0, v121
	v_max_f32_e32 v122, 0, v122
	v_max_f32_e32 v124, 0, v124
	v_mul_f32_e32 v120, v120, v120
	v_mul_f32_e32 v125, v121, v121
	v_max_f32_e32 v121, 0, v126
	v_mul_f32_e32 v126, v122, v122
	v_max_f32_e32 v122, 0, v127
	v_max_f32_e32 v123, 0, v123
	v_pk_mul_f32 v[114:115], v[114:115], v[150:151] op_sel_hi:[1,0]
	v_pk_mul_f32 v[112:113], v[112:113], v[150:151] op_sel_hi:[1,0]
	v_mul_f32_e32 v124, v124, v124
	v_mul_f32_e32 v121, v121, v121
	v_mul_f32_e32 v122, v122, v122
	v_mul_f32_e32 v123, v123, v123
	v_cvt_pk_bf16_f32 v120, v124, v120
	v_pk_mul_f32 v[118:119], v[118:119], v[150:151] op_sel_hi:[1,0]
	v_pk_mul_f32 v[116:117], v[116:117], v[150:151] op_sel_hi:[1,0]
	v_max_f32_e32 v112, 0, v112
	v_max_f32_e32 v113, 0, v113
	v_max_f32_e32 v114, 0, v114
	v_cvt_pk_bf16_f32 v121, v121, v122
	v_cvt_pk_bf16_f32 v122, v149, v125
	v_cvt_pk_bf16_f32 v123, v126, v123
	global_store_dwordx4 v[134:135], v[120:123], off
	v_max_f32_e32 v116, 0, v116
	v_max_f32_e32 v115, 0, v115
	v_mul_f32_e32 v120, v112, v112
	v_max_f32_e32 v112, 0, v117
	v_mul_f32_e32 v117, v113, v113
	v_max_f32_e32 v113, 0, v118
	v_mul_f32_e32 v118, v114, v114
	v_max_f32_e32 v114, 0, v119
	v_mul_f32_e32 v112, v112, v112
	v_mul_f32_e32 v113, v113, v113
	v_mul_f32_e32 v114, v114, v114
	v_mul_f32_e32 v116, v116, v116
	v_mul_f32_e32 v115, v115, v115
	v_cvt_pk_bf16_f32 v112, v116, v112
	v_cvt_pk_bf16_f32 v113, v113, v114
	v_cvt_pk_bf16_f32 v114, v120, v117
	v_cvt_pk_bf16_f32 v115, v118, v115
	global_store_dwordx4 v[134:135], v[112:115], off offset:256
	s_nop 1
	v_fmamk_f32 v114, v151, 0x3a000000, v227
	v_rsq_f32_e32 v114, v114
	v_lshlrev_b64 v[112:113], 14, v[142:143]
	v_lshl_add_u64 v[112:113], v[138:139], 0, v[112:113]
	v_pk_mul_f32 v[104:105], v[104:105], v[114:115] op_sel_hi:[1,0]
	v_pk_mul_f32 v[108:109], v[108:109], v[114:115] op_sel_hi:[1,0]
	v_pk_mul_f32 v[106:107], v[106:107], v[114:115] op_sel_hi:[1,0]
	v_max_f32_e32 v104, 0, v104
	v_pk_mul_f32 v[110:111], v[110:111], v[114:115] op_sel_hi:[1,0]
	v_mul_f32_e32 v115, v104, v104
	v_max_f32_e32 v104, 0, v109
	v_max_f32_e32 v105, 0, v105
	v_max_f32_e32 v106, 0, v106
	v_max_f32_e32 v108, 0, v108
	v_mul_f32_e32 v104, v104, v104
	v_mul_f32_e32 v109, v105, v105
	v_max_f32_e32 v105, 0, v110
	v_mul_f32_e32 v110, v106, v106
	v_max_f32_e32 v106, 0, v111
	v_max_f32_e32 v107, 0, v107
	v_pk_mul_f32 v[98:99], v[98:99], v[114:115] op_sel_hi:[1,0]
	v_pk_mul_f32 v[96:97], v[96:97], v[114:115] op_sel_hi:[1,0]
	v_mul_f32_e32 v108, v108, v108
	v_mul_f32_e32 v105, v105, v105
	v_mul_f32_e32 v106, v106, v106
	v_mul_f32_e32 v107, v107, v107
	v_cvt_pk_bf16_f32 v104, v108, v104
	v_pk_mul_f32 v[102:103], v[102:103], v[114:115] op_sel_hi:[1,0]
	v_pk_mul_f32 v[100:101], v[100:101], v[114:115] op_sel_hi:[1,0]
	v_max_f32_e32 v96, 0, v96
	v_max_f32_e32 v97, 0, v97
	v_max_f32_e32 v98, 0, v98
	v_cvt_pk_bf16_f32 v105, v105, v106
	v_cvt_pk_bf16_f32 v106, v115, v109
	v_cvt_pk_bf16_f32 v107, v110, v107
	global_store_dwordx4 v[112:113], v[104:107], off
	v_max_f32_e32 v100, 0, v100
	v_max_f32_e32 v99, 0, v99
	v_mul_f32_e32 v104, v96, v96
	v_max_f32_e32 v96, 0, v101
	v_mul_f32_e32 v101, v97, v97
	v_max_f32_e32 v97, 0, v102
	v_mul_f32_e32 v102, v98, v98
	v_max_f32_e32 v98, 0, v103
	v_mul_f32_e32 v96, v96, v96
	v_mul_f32_e32 v97, v97, v97
	v_mul_f32_e32 v98, v98, v98
	v_mul_f32_e32 v100, v100, v100
	v_mul_f32_e32 v99, v99, v99
	v_cvt_pk_bf16_f32 v96, v100, v96
	v_cvt_pk_bf16_f32 v97, v97, v98
	v_cvt_pk_bf16_f32 v98, v104, v101
	v_cvt_pk_bf16_f32 v99, v102, v99
	global_store_dwordx4 v[112:113], v[96:99], off offset:256
;     __device__ __forceinline__ const char* a(const Unit& u) const { return (const char*)A + (size_t)u.pm * 2 * hA(); }
;     __device__ __forceinline__ const char* b(const Unit& u) const { return (const char*)Bt + (size_t)u.pn * 2 * hB() + (size_t)(u.pm >> gshift) * goff; }
;     __device__ __forceinline__ const char* a(const Unit& u) const { return (const char*)A + (size_t)u.pm * 2 * hA(); }
;     __device__ __forceinline__ const char* b(const Unit& u) const { return (const char*)Bt + (size_t)((u.pn >> 4) * 4096 + (u.pn & 15) * 16) * 1024 * 2 + (size_t)(u.pm >> 1) * 512; }
;     __device__ __forceinline__ const char* a(const Unit&) const { return (const char*)A; }
;     __device__ __forceinline__ const char* b(const Unit& u) const { return (const char*)Bt + ((size_t)(((u.pm >> 4) * 1024 + u.pn * 256) * 16 + (u.pm & 15)) * 512) * 2; }
;     __device__ __forceinline__ void operator()(const f32x4 (&acc)[2][2][4][2], const Unit& u, int wr, int wc, int fr, int fq) const {
;     ...
;         for (int ai = 0; ai < 2; ++ai)
; #pragma unroll
;             for (int m = 0; m < 4; ++m) { const int r = row0 + ai * HALF + m * 16;
;                 bf16_t* rowp = hm ? base + ((size_t)((r >> 12) * 8 + (colt >> 7)) * 4096 + (r & 4095)) * 128 + wc * 32 + 8 * fq : base + (size_t)r * ldc + col0;
;                 float rv = sc; if (RS == 1) rv *= rsv[ai][m]; if (RS == 2) rv *= __builtin_amdgcn_rsqf(rsv[ai][m] * (1.0f / DM) + EPS);
; #pragma unroll
;                 for (int bj = 0; bj < 2; ++bj) { f32x4 v0 = acc[ai][bj][m][0] * rv, v1 = acc[ai][bj][m][1] * rv;
;                     if (CS) { v0 = v0 * cv[bj][0]; v1 = v1 * cv[bj][1]; }
;                     if (ACT == 2) {
; #pragma unroll
;                         for (int e = 0; e < 4; ++e) { float a = v0[e] > 0.f ? v0[e] : 0.f, b = v1[e] > 0.f ? v1[e] : 0.f; v0[e] = a * a; v1[e] = b * b; } }
;                     if (k8) {
;                         u32x2 w8; w8.x = pk_fp8x4(v0); w8.y = pk_fp8x4(v1);
;                         *(u32x2*)((unsigned char*)base + ((size_t)((r >> 12) * 8 + (colt >> 7) + bj) * 4096 + (r & 4095)) * 128 + wc * 32 + 8 * fq) = w8;
;                     } else {
;                     u32x4 w; w.x = cvt_pk_bf16(v0[0], v0[1]); w.y = cvt_pk_bf16(v0[2], v0[3]); w.z = cvt_pk_bf16(v1[0], v1[1]); w.w = cvt_pk_bf16(v1[2], v1[3]);
;                     *(u32x4*)(rowp + bj * bstep) = w; } } }
	s_nop 1
	v_fmamk_f32 v98, v148, 0x3a000000, v227
	v_rsq_f32_e32 v98, v98
	v_lshlrev_b64 v[96:97], 14, v[140:141]
	v_lshl_add_u64 v[96:97], v[138:139], 0, v[96:97]
	v_pk_mul_f32 v[88:89], v[88:89], v[98:99] op_sel_hi:[1,0]
	v_pk_mul_f32 v[92:93], v[92:93], v[98:99] op_sel_hi:[1,0]
	v_pk_mul_f32 v[90:91], v[90:91], v[98:99] op_sel_hi:[1,0]
	v_max_f32_e32 v88, 0, v88
	v_pk_mul_f32 v[94:95], v[94:95], v[98:99] op_sel_hi:[1,0]
	v_mul_f32_e32 v99, v88, v88
	v_max_f32_e32 v88, 0, v93
	v_max_f32_e32 v89, 0, v89
	v_max_f32_e32 v90, 0, v90
	v_max_f32_e32 v92, 0, v92
	v_mul_f32_e32 v88, v88, v88
	v_mul_f32_e32 v93, v89, v89
	v_max_f32_e32 v89, 0, v94
	v_mul_f32_e32 v94, v90, v90
	v_max_f32_e32 v90, 0, v95
	v_max_f32_e32 v91, 0, v91
	v_pk_mul_f32 v[82:83], v[82:83], v[98:99] op_sel_hi:[1,0]
	v_pk_mul_f32 v[80:81], v[80:81], v[98:99] op_sel_hi:[1,0]
	v_mul_f32_e32 v92, v92, v92
	v_mul_f32_e32 v89, v89, v89
	v_mul_f32_e32 v90, v90, v90
	v_mul_f32_e32 v91, v91, v91
	v_cvt_pk_bf16_f32 v88, v92, v88
	v_pk_mul_f32 v[86:87], v[86:87], v[98:99] op_sel_hi:[1,0]
	v_pk_mul_f32 v[84:85], v[84:85], v[98:99] op_sel_hi:[1,0]
	v_max_f32_e32 v80, 0, v80
	v_max_f32_e32 v81, 0, v81
	v_max_f32_e32 v82, 0, v82
	v_cvt_pk_bf16_f32 v89, v89, v90
	v_cvt_pk_bf16_f32 v90, v99, v93
	v_cvt_pk_bf16_f32 v91, v94, v91
	global_store_dwordx4 v[96:97], v[88:91], off
	v_max_f32_e32 v84, 0, v84
	v_max_f32_e32 v83, 0, v83
	v_mul_f32_e32 v88, v80, v80
	v_max_f32_e32 v80, 0, v85
	v_mul_f32_e32 v85, v81, v81
	v_max_f32_e32 v81, 0, v86
	v_mul_f32_e32 v86, v82, v82
	v_max_f32_e32 v82, 0, v87
	v_mul_f32_e32 v80, v80, v80
	v_mul_f32_e32 v81, v81, v81
	v_mul_f32_e32 v82, v82, v82
	v_mul_f32_e32 v84, v84, v84
	v_mul_f32_e32 v83, v83, v83
	v_cvt_pk_bf16_f32 v80, v84, v80
	v_cvt_pk_bf16_f32 v81, v81, v82
	v_cvt_pk_bf16_f32 v82, v88, v85
	v_cvt_pk_bf16_f32 v83, v86, v83
	global_store_dwordx4 v[96:97], v[80:83], off offset:256
	s_nop 1
	v_fmamk_f32 v82, v147, 0x3a000000, v227
	v_rsq_f32_e32 v82, v82
	v_lshlrev_b64 v[80:81], 14, v[136:137]
	v_lshl_add_u64 v[80:81], v[138:139], 0, v[80:81]
	v_pk_mul_f32 v[72:73], v[72:73], v[82:83] op_sel_hi:[1,0]
	v_pk_mul_f32 v[76:77], v[76:77], v[82:83] op_sel_hi:[1,0]
	v_pk_mul_f32 v[74:75], v[74:75], v[82:83] op_sel_hi:[1,0]
	v_max_f32_e32 v72, 0, v72
	v_pk_mul_f32 v[78:79], v[78:79], v[82:83] op_sel_hi:[1,0]
	v_mul_f32_e32 v83, v72, v72
	v_max_f32_e32 v72, 0, v77
	v_max_f32_e32 v73, 0, v73
	v_max_f32_e32 v74, 0, v74
	v_max_f32_e32 v76, 0, v76
	v_mul_f32_e32 v72, v72, v72
	v_mul_f32_e32 v77, v73, v73
	v_max_f32_e32 v73, 0, v78
	v_mul_f32_e32 v78, v74, v74
	v_max_f32_e32 v74, 0, v79
	v_max_f32_e32 v75, 0, v75
	v_pk_mul_f32 v[66:67], v[66:67], v[82:83] op_sel_hi:[1,0]
	v_pk_mul_f32 v[64:65], v[64:65], v[82:83] op_sel_hi:[1,0]
	v_mul_f32_e32 v76, v76, v76
	v_mul_f32_e32 v73, v73, v73
	v_mul_f32_e32 v74, v74, v74
	v_mul_f32_e32 v75, v75, v75
	v_cvt_pk_bf16_f32 v72, v76, v72
	v_pk_mul_f32 v[70:71], v[70:71], v[82:83] op_sel_hi:[1,0]
	v_pk_mul_f32 v[68:69], v[68:69], v[82:83] op_sel_hi:[1,0]
	v_max_f32_e32 v64, 0, v64
	v_max_f32_e32 v65, 0, v65
	v_max_f32_e32 v66, 0, v66
	v_cvt_pk_bf16_f32 v73, v73, v74
	v_cvt_pk_bf16_f32 v74, v83, v77
	v_cvt_pk_bf16_f32 v75, v78, v75
	global_store_dwordx4 v[80:81], v[72:75], off
	v_max_f32_e32 v68, 0, v68
	v_max_f32_e32 v67, 0, v67
	v_mul_f32_e32 v72, v64, v64
	v_max_f32_e32 v64, 0, v69
	v_mul_f32_e32 v69, v65, v65
	v_max_f32_e32 v65, 0, v70
	v_mul_f32_e32 v70, v66, v66
	v_max_f32_e32 v66, 0, v71
	v_mul_f32_e32 v64, v64, v64
	v_mul_f32_e32 v65, v65, v65
	v_mul_f32_e32 v66, v66, v66
	v_mul_f32_e32 v68, v68, v68
	v_mul_f32_e32 v67, v67, v67
	v_cvt_pk_bf16_f32 v64, v68, v64
	v_cvt_pk_bf16_f32 v65, v65, v66
	v_cvt_pk_bf16_f32 v66, v72, v69
	v_cvt_pk_bf16_f32 v67, v70, v67
	global_store_dwordx4 v[80:81], v[64:67], off offset:256
	s_nop 1
	v_fmamk_f32 v66, v146, 0x3a000000, v227
	v_rsq_f32_e32 v66, v66
	v_lshl_add_u64 v[64:65], v[134:135], 0, s[22:23]
	s_mov_b64 s[22:23], 0x240000
	v_pk_mul_f32 v[56:57], v[56:57], v[66:67] op_sel_hi:[1,0]
	v_pk_mul_f32 v[60:61], v[60:61], v[66:67] op_sel_hi:[1,0]
	v_pk_mul_f32 v[58:59], v[58:59], v[66:67] op_sel_hi:[1,0]
	v_max_f32_e32 v56, 0, v56
	v_pk_mul_f32 v[62:63], v[62:63], v[66:67] op_sel_hi:[1,0]
	v_max_f32_e32 v60, 0, v60
	v_mul_f32_e32 v67, v56, v56
	v_max_f32_e32 v56, 0, v61
	v_max_f32_e32 v57, 0, v57
	v_max_f32_e32 v58, 0, v58
	v_mul_f32_e32 v60, v60, v60
	v_mul_f32_e32 v56, v56, v56
	v_mul_f32_e32 v61, v57, v57
	v_max_f32_e32 v57, 0, v62
	v_mul_f32_e32 v62, v58, v58
	v_max_f32_e32 v58, 0, v63
	v_mul_f32_e32 v57, v57, v57
	v_max_f32_e32 v59, 0, v59
	v_mul_f32_e32 v58, v58, v58
	v_cvt_pk_bf16_f32 v56, v60, v56
	v_add_co_u32_e32 v60, vcc, s21, v134
	v_pk_mul_f32 v[50:51], v[50:51], v[66:67] op_sel_hi:[1,0]
	v_pk_mul_f32 v[48:49], v[48:49], v[66:67] op_sel_hi:[1,0]
	v_mul_f32_e32 v59, v59, v59
	v_cvt_pk_bf16_f32 v57, v57, v58
	v_cvt_pk_bf16_f32 v58, v67, v61
	v_addc_co_u32_e32 v61, vcc, 0, v135, vcc
	v_pk_mul_f32 v[54:55], v[54:55], v[66:67] op_sel_hi:[1,0]
	v_pk_mul_f32 v[52:53], v[52:53], v[66:67] op_sel_hi:[1,0]
	v_max_f32_e32 v48, 0, v48
	v_max_f32_e32 v49, 0, v49
	v_max_f32_e32 v50, 0, v50
	v_cvt_pk_bf16_f32 v59, v62, v59
	global_store_dwordx4 v[60:61], v[56:59], off
	v_max_f32_e32 v52, 0, v52
	v_max_f32_e32 v51, 0, v51
	v_mul_f32_e32 v56, v48, v48
	v_max_f32_e32 v48, 0, v53
	v_mul_f32_e32 v53, v49, v49
	v_max_f32_e32 v49, 0, v54
	v_mul_f32_e32 v54, v50, v50
	v_max_f32_e32 v50, 0, v55
	v_mul_f32_e32 v48, v48, v48
	v_mul_f32_e32 v49, v49, v49
	v_mul_f32_e32 v50, v50, v50
	v_mul_f32_e32 v52, v52, v52
	v_mul_f32_e32 v51, v51, v51
	v_cvt_pk_bf16_f32 v48, v52, v48
	v_cvt_pk_bf16_f32 v49, v49, v50
;     __device__ __forceinline__ const char* a(const Unit& u) const { return (const char*)A + (size_t)u.pm * 2 * hA(); }
;     __device__ __forceinline__ const char* b(const Unit& u) const { return (const char*)Bt + (size_t)u.pn * 2 * hB() + (size_t)(u.pm >> gshift) * goff; }
;     __device__ __forceinline__ const char* a(const Unit& u) const { return (const char*)A + (size_t)u.pm * 2 * hA(); }
;     __device__ __forceinline__ const char* b(const Unit& u) const { return (const char*)Bt + (size_t)((u.pn >> 4) * 4096 + (u.pn & 15) * 16) * 1024 * 2 + (size_t)(u.pm >> 1) * 512; }
;     __device__ __forceinline__ const char* a(const Unit&) const { return (const char*)A; }
;     __device__ __forceinline__ const char* b(const Unit& u) const { return (const char*)Bt + ((size_t)(((u.pm >> 4) * 1024 + u.pn * 256) * 16 + (u.pm & 15)) * 512) * 2; }
;     __device__ __forceinline__ void operator()(const f32x4 (&acc)[2][2][4][2], const Unit& u, int wr, int wc, int fr, int fq) const {
;     ...
;         for (int ai = 0; ai < 2; ++ai)
; #pragma unroll
;             for (int m = 0; m < 4; ++m) { const int r = row0 + ai * HALF + m * 16;
;                 bf16_t* rowp = hm ? base + ((size_t)((r >> 12) * 8 + (colt >> 7)) * 4096 + (r & 4095)) * 128 + wc * 32 + 8 * fq : base + (size_t)r * ldc + col0;
;                 float rv = sc; if (RS == 1) rv *= rsv[ai][m]; if (RS == 2) rv *= __builtin_amdgcn_rsqf(rsv[ai][m] * (1.0f / DM) + EPS);
; #pragma unroll
;                 for (int bj = 0; bj < 2; ++bj) { f32x4 v0 = acc[ai][bj][m][0] * rv, v1 = acc[ai][bj][m][1] * rv;
;                     if (CS) { v0 = v0 * cv[bj][0]; v1 = v1 * cv[bj][1]; }
;                     if (ACT == 2) {
; #pragma unroll
;                         for (int e = 0; e < 4; ++e) { float a = v0[e] > 0.f ? v0[e] : 0.f, b = v1[e] > 0.f ? v1[e] : 0.f; v0[e] = a * a; v1[e] = b * b; } }
;                     if (k8) {
;                         u32x2 w8; w8.x = pk_fp8x4(v0); w8.y = pk_fp8x4(v1);
;                         *(u32x2*)((unsigned char*)base + ((size_t)((r >> 12) * 8 + (colt >> 7) + bj) * 4096 + (r & 4095)) * 128 + wc * 32 + 8 * fq) = w8;
;                     } else {
;                     u32x4 w; w.x = cvt_pk_bf16(v0[0], v0[1]); w.y = cvt_pk_bf16(v0[2], v0[3]); w.z = cvt_pk_bf16(v1[0], v1[1]); w.w = cvt_pk_bf16(v1[2], v1[3]);
;                     *(u32x4*)(rowp + bj * bstep) = w; } } }
	v_cvt_pk_bf16_f32 v50, v56, v53
	v_cvt_pk_bf16_f32 v51, v54, v51
	global_store_dwordx4 v[64:65], v[48:51], off offset:256
	s_mov_b32 s21, 0x240000
	s_nop 0
	v_fmamk_f32 v50, v145, 0x3a000000, v227
	v_rsq_f32_e32 v50, v50
	v_lshl_add_u64 v[48:49], v[134:135], 0, s[22:23]
	s_mov_b64 s[22:23], 0x280000
	v_pk_mul_f32 v[40:41], v[40:41], v[50:51] op_sel_hi:[1,0]
	v_pk_mul_f32 v[44:45], v[44:45], v[50:51] op_sel_hi:[1,0]
	v_pk_mul_f32 v[42:43], v[42:43], v[50:51] op_sel_hi:[1,0]
	v_max_f32_e32 v40, 0, v40
	v_pk_mul_f32 v[46:47], v[46:47], v[50:51] op_sel_hi:[1,0]
	v_max_f32_e32 v44, 0, v44
	v_mul_f32_e32 v51, v40, v40
	v_max_f32_e32 v40, 0, v45
	v_max_f32_e32 v41, 0, v41
	v_max_f32_e32 v42, 0, v42
	v_mul_f32_e32 v44, v44, v44
	v_mul_f32_e32 v40, v40, v40
	v_mul_f32_e32 v45, v41, v41
	v_max_f32_e32 v41, 0, v46
	v_mul_f32_e32 v46, v42, v42
	v_max_f32_e32 v42, 0, v47
	v_mul_f32_e32 v41, v41, v41
	v_max_f32_e32 v43, 0, v43
	v_mul_f32_e32 v42, v42, v42
	v_cvt_pk_bf16_f32 v40, v44, v40
	v_add_co_u32_e32 v44, vcc, s21, v134
	v_pk_mul_f32 v[34:35], v[34:35], v[50:51] op_sel_hi:[1,0]
	v_pk_mul_f32 v[32:33], v[32:33], v[50:51] op_sel_hi:[1,0]
	v_mul_f32_e32 v43, v43, v43
	v_cvt_pk_bf16_f32 v41, v41, v42
	v_cvt_pk_bf16_f32 v42, v51, v45
	v_addc_co_u32_e32 v45, vcc, 0, v135, vcc
	v_pk_mul_f32 v[38:39], v[38:39], v[50:51] op_sel_hi:[1,0]
	v_pk_mul_f32 v[36:37], v[36:37], v[50:51] op_sel_hi:[1,0]
	v_max_f32_e32 v32, 0, v32
	v_max_f32_e32 v33, 0, v33
	v_max_f32_e32 v34, 0, v34
	v_cvt_pk_bf16_f32 v43, v46, v43
	global_store_dwordx4 v[44:45], v[40:43], off
	v_max_f32_e32 v36, 0, v36
	v_max_f32_e32 v35, 0, v35
	v_mul_f32_e32 v40, v32, v32
	v_max_f32_e32 v32, 0, v37
	v_mul_f32_e32 v37, v33, v33
	v_max_f32_e32 v33, 0, v38
	v_mul_f32_e32 v38, v34, v34
	v_max_f32_e32 v34, 0, v39
	v_mul_f32_e32 v32, v32, v32
	v_mul_f32_e32 v33, v33, v33
	v_mul_f32_e32 v34, v34, v34
	v_mul_f32_e32 v36, v36, v36
	v_mul_f32_e32 v35, v35, v35
	v_cvt_pk_bf16_f32 v32, v36, v32
	v_cvt_pk_bf16_f32 v33, v33, v34
	v_cvt_pk_bf16_f32 v34, v40, v37
	v_cvt_pk_bf16_f32 v35, v38, v35
	global_store_dwordx4 v[48:49], v[32:35], off offset:256
	s_mov_b32 s21, 0x280000
	s_nop 0
	v_fmamk_f32 v34, v144, 0x3a000000, v227
	v_rsq_f32_e32 v34, v34
	v_lshl_add_u64 v[32:33], v[134:135], 0, s[22:23]
	s_mov_b64 s[22:23], 0x2c0000
	v_pk_mul_f32 v[24:25], v[24:25], v[34:35] op_sel_hi:[1,0]
	v_pk_mul_f32 v[28:29], v[28:29], v[34:35] op_sel_hi:[1,0]
	v_pk_mul_f32 v[26:27], v[26:27], v[34:35] op_sel_hi:[1,0]
	v_max_f32_e32 v24, 0, v24
	v_pk_mul_f32 v[30:31], v[30:31], v[34:35] op_sel_hi:[1,0]
	v_max_f32_e32 v28, 0, v28
	v_mul_f32_e32 v35, v24, v24
	v_max_f32_e32 v24, 0, v29
	v_max_f32_e32 v25, 0, v25
	v_max_f32_e32 v26, 0, v26
	v_mul_f32_e32 v28, v28, v28
	v_mul_f32_e32 v24, v24, v24
	v_mul_f32_e32 v29, v25, v25
	v_max_f32_e32 v25, 0, v30
	v_mul_f32_e32 v30, v26, v26
	v_max_f32_e32 v26, 0, v31
	v_mul_f32_e32 v25, v25, v25
	v_max_f32_e32 v27, 0, v27
	v_mul_f32_e32 v26, v26, v26
	v_cvt_pk_bf16_f32 v24, v28, v24
	v_add_co_u32_e32 v28, vcc, s21, v134
	v_pk_mul_f32 v[18:19], v[18:19], v[34:35] op_sel_hi:[1,0]
	v_pk_mul_f32 v[16:17], v[16:17], v[34:35] op_sel_hi:[1,0]
	v_mul_f32_e32 v27, v27, v27
	v_cvt_pk_bf16_f32 v25, v25, v26
	v_cvt_pk_bf16_f32 v26, v35, v29
	v_addc_co_u32_e32 v29, vcc, 0, v135, vcc
	v_pk_mul_f32 v[22:23], v[22:23], v[34:35] op_sel_hi:[1,0]
	v_pk_mul_f32 v[20:21], v[20:21], v[34:35] op_sel_hi:[1,0]
	v_max_f32_e32 v16, 0, v16
	v_max_f32_e32 v17, 0, v17
	v_max_f32_e32 v18, 0, v18
	v_cvt_pk_bf16_f32 v27, v30, v27
	global_store_dwordx4 v[28:29], v[24:27], off
	v_max_f32_e32 v20, 0, v20
	v_max_f32_e32 v19, 0, v19
	v_mul_f32_e32 v24, v16, v16
	v_max_f32_e32 v16, 0, v21
	v_mul_f32_e32 v21, v17, v17
	v_max_f32_e32 v17, 0, v22
	v_mul_f32_e32 v22, v18, v18
	v_max_f32_e32 v18, 0, v23
	v_mul_f32_e32 v16, v16, v16
	v_mul_f32_e32 v17, v17, v17
	v_mul_f32_e32 v18, v18, v18
	v_mul_f32_e32 v20, v20, v20
	v_mul_f32_e32 v19, v19, v19
	v_cvt_pk_bf16_f32 v16, v20, v16
	v_cvt_pk_bf16_f32 v17, v17, v18
	v_cvt_pk_bf16_f32 v18, v24, v21
	v_cvt_pk_bf16_f32 v19, v22, v19
	global_store_dwordx4 v[32:33], v[16:19], off offset:256
	s_mov_b32 s21, 0x2c0000
	s_nop 0
	v_fmamk_f32 v18, v133, 0x3a000000, v227
	v_rsq_f32_e32 v18, v18
	v_lshl_add_u64 v[16:17], v[134:135], 0, s[22:23]
	s_mov_b64 s[22:23], -1
	v_pk_mul_f32 v[8:9], v[8:9], v[18:19] op_sel_hi:[1,0]
	v_pk_mul_f32 v[12:13], v[12:13], v[18:19] op_sel_hi:[1,0]
	v_pk_mul_f32 v[10:11], v[10:11], v[18:19] op_sel_hi:[1,0]
	v_max_f32_e32 v8, 0, v8
	v_pk_mul_f32 v[14:15], v[14:15], v[18:19] op_sel_hi:[1,0]
	v_max_f32_e32 v12, 0, v12
	v_mul_f32_e32 v19, v8, v8
	v_max_f32_e32 v8, 0, v13
	v_max_f32_e32 v9, 0, v9
	v_max_f32_e32 v10, 0, v10
	v_mul_f32_e32 v12, v12, v12
	v_mul_f32_e32 v8, v8, v8
	v_mul_f32_e32 v13, v9, v9
	v_max_f32_e32 v9, 0, v14
	v_mul_f32_e32 v14, v10, v10
	v_max_f32_e32 v10, 0, v15
	v_mul_f32_e32 v9, v9, v9
	v_max_f32_e32 v11, 0, v11
	v_mul_f32_e32 v10, v10, v10
	v_cvt_pk_bf16_f32 v8, v12, v8
	v_add_co_u32_e32 v12, vcc, s21, v134
	v_pk_mul_f32 v[2:3], v[2:3], v[18:19] op_sel_hi:[1,0]
	v_pk_mul_f32 v[0:1], v[0:1], v[18:19] op_sel_hi:[1,0]
	v_mul_f32_e32 v11, v11, v11
	v_cvt_pk_bf16_f32 v9, v9, v10
	v_cvt_pk_bf16_f32 v10, v19, v13
	v_addc_co_u32_e32 v13, vcc, 0, v135, vcc
	v_pk_mul_f32 v[6:7], v[6:7], v[18:19] op_sel_hi:[1,0]
	v_pk_mul_f32 v[4:5], v[4:5], v[18:19] op_sel_hi:[1,0]
	v_max_f32_e32 v0, 0, v0
	v_max_f32_e32 v1, 0, v1
	v_max_f32_e32 v2, 0, v2
	v_cvt_pk_bf16_f32 v11, v14, v11
	global_store_dwordx4 v[12:13], v[8:11], off
	v_max_f32_e32 v3, 0, v3
	v_max_f32_e32 v4, 0, v4
	v_mul_f32_e32 v8, v0, v0
	v_max_f32_e32 v0, 0, v5
	v_mul_f32_e32 v5, v1, v1
	v_max_f32_e32 v1, 0, v6
	v_mul_f32_e32 v6, v2, v2
	v_max_f32_e32 v2, 0, v7
	v_mul_f32_e32 v0, v0, v0
	v_mul_f32_e32 v1, v1, v1
	v_mul_f32_e32 v2, v2, v2
	v_mul_f32_e32 v3, v3, v3
	s_andn2_b64 vcc, exec, s[40:41]
	v_mul_f32_e32 v4, v4, v4
	v_cvt_pk_bf16_f32 v0, v4, v0
	v_cvt_pk_bf16_f32 v1, v1, v2
	v_cvt_pk_bf16_f32 v2, v8, v5
	v_cvt_pk_bf16_f32 v3, v6, v3
	global_store_dwordx4 v[16:17], v[0:3], off offset:256
	s_cbranch_vccnz .LBB0_708
	s_and_b64 vcc, exec, s[38:39]
	s_cbranch_vccnz .LBB0_707
	s_barrier
	s_branch .LBB0_707

; __global__ void __launch_bounds__(NWAVES * 64, 2) mk_fwd(Args args) {
	.amdhsa_kernel _Z6mk_fwd4Args
		.amdhsa_group_segment_fixed_size 0
		.amdhsa_private_segment_fixed_size 0
		.amdhsa_kernarg_size 344
		.amdhsa_user_sgpr_count 2
		.amdhsa_user_sgpr_dispatch_ptr 0
		.amdhsa_user_sgpr_queue_ptr 0
		.amdhsa_user_sgpr_kernarg_segment_ptr 1
		.amdhsa_user_sgpr_dispatch_id 0
		.amdhsa_user_sgpr_kernarg_preload_length 0
		.amdhsa_user_sgpr_kernarg_preload_offset 0
		.amdhsa_user_sgpr_private_segment_size 0
		.amdhsa_uses_dynamic_stack 0
		.amdhsa_enable_private_segment 0
		.amdhsa_system_sgpr_workgroup_id_x 1
		.amdhsa_system_sgpr_workgroup_id_y 0
		.amdhsa_system_sgpr_workgroup_id_z 0
		.amdhsa_system_sgpr_workgroup_info 0
		.amdhsa_system_vgpr_workitem_id 0
		.amdhsa_next_free_vgpr 256
		.amdhsa_next_free_sgpr 102
		.amdhsa_accum_offset 256
		.amdhsa_reserve_vcc 1
		.amdhsa_float_round_mode_32 0
		.amdhsa_float_round_mode_16_64 0
		.amdhsa_float_denorm_mode_32 3
		.amdhsa_float_denorm_mode_16_64 3
		.amdhsa_dx10_clamp 1
		.amdhsa_ieee_mode 1
		.amdhsa_fp16_overflow 0
		.amdhsa_tg_split 0
		.amdhsa_exception_fp_ieee_invalid_op 0
		.amdhsa_exception_fp_denorm_src 0
		.amdhsa_exception_fp_ieee_div_zero 0
		.amdhsa_exception_fp_ieee_overflow 0
		.amdhsa_exception_fp_ieee_underflow 0
		.amdhsa_exception_fp_ieee_inexact 0
		.amdhsa_exception_int_div_zero 0
	.end_amdhsa_kernel

; __global__ void __launch_bounds__(NWAVES * 64, 2) mk_fwd(Args args) {
amdhsa.kernels:
  - .agpr_count:     0
    .args:
      - .offset:         0
        .size:           88
        .value_kind:     by_value
      - .offset:         88
        .size:           4
        .value_kind:     hidden_block_count_x
      - .offset:         92
        .size:           4
        .value_kind:     hidden_block_count_y
      - .offset:         96
        .size:           4
        .value_kind:     hidden_block_count_z
      - .offset:         100
        .size:           2
        .value_kind:     hidden_group_size_x
      - .offset:         102
        .size:           2
        .value_kind:     hidden_group_size_y
      - .offset:         104
        .size:           2
        .value_kind:     hidden_group_size_z
      - .offset:         106
        .size:           2
        .value_kind:     hidden_remainder_x
      - .offset:         108
        .size:           2
        .value_kind:     hidden_remainder_y
      - .offset:         110
        .size:           2
        .value_kind:     hidden_remainder_z
      - .offset:         128
        .size:           8
        .value_kind:     hidden_global_offset_x
      - .offset:         136
        .size:           8
        .value_kind:     hidden_global_offset_y
      - .offset:         144
        .size:           8
        .value_kind:     hidden_global_offset_z
      - .offset:         152
        .size:           2
        .value_kind:     hidden_grid_dims
      - .offset:         208
        .size:           4
        .value_kind:     hidden_dynamic_lds_size
    .group_segment_fixed_size: 0
    .kernarg_segment_align: 8
    .kernarg_segment_size: 344
    .language:       OpenCL C
    .language_version:
      - 2
      - 0
    .max_flat_workgroup_size: 512
    .name:           _Z6mk_fwd4Args
    .private_segment_fixed_size: 0
    .sgpr_count:     108
    .sgpr_spill_count: 128
    .symbol:         _Z6mk_fwd4Args.kd
    .uniform_work_group_size: 1
    .uses_dynamic_stack: false
    .vgpr_count:     256
    .vgpr_spill_count: 0
    .wavefront_size: 64
